# attention softmax: row-max via 8 v_max3 per row tile (dropped redundant self-max canonicalisations), on top of swizzled K/V LDS layout and wave stagger
# speedup vs baseline: 1.0066x; 1.0066x over previous
; #define LAS __attribute__((address_space(3)))
; template <int MASK> ...
;     ...
;     for (int np = 0; np < 2; ++np) {
;         bf16x8 kf[2][4];
; #pragma unroll
;         for (int n2 = 0; n2 < 2; ++n2)
; #pragma unroll
;             for (int kk = 0; kk < 4; ++kk) kf[n2][kk] = *(const LAS bf16x8*)(Kl + ((np * 2 + n2) * 16 + i16) * 136 + kk * 32 + quad * 8);
;         __builtin_amdgcn_sched_barrier(0);
; #pragma unroll
;         for (int n2 = 0; n2 < 2; ++n2) { s[0][np * 2 + n2] = (f32x4){bias0, bias0, bias0, bias0}; s[1][np * 2 + n2] = (f32x4){bias1, bias1, bias1, bias1}; }
; #pragma unroll
;         for (int kk = 0; kk < 4; ++kk)
; #pragma unroll
;             for (int n2 = 0; n2 < 2; ++n2) {
;                 if (MASK & 1) s[0][np * 2 + n2] = __builtin_amdgcn_mfma_f32_16x16x32_bf16(kf[n2][kk], q[0][kk], s[0][np * 2 + n2], 0, 0, 0);
;                 if (MASK & 2) s[1][np * 2 + n2] = __builtin_amdgcn_mfma_f32_16x16x32_bf16(kf[n2][kk], q[1][kk], s[1][np * 2 + n2], 0, 0, 0); }
;     }
;     u32x2 vlo0[8], vhi0[8];
; #pragma unroll
;     for (int dt = 0; dt < 8; ++dt) { const u32x4 vq = *(const LAS u32x4*)(Vl + (dt * 16 + i16) * 72 + quad * 8); vlo0[dt] = (u32x2){vq.x, vq.y}; vhi0[dt] = (u32x2){vq.z, vq.w}; }
;     __builtin_amdgcn_sched_barrier(0);
;     bf16x8 pa[2][2];
; #pragma unroll
;     for (int rt = 0; rt < 2; ++rt) {
;         if (!(MASK & (1 << rt))) continue;
;         const int t = t0 + rt * 4 + tl;
;         float tmx = -1e30f;
;         if (edge) {
; #pragma unroll
;             for (int nt = 0; nt < 4; ++nt)
; #pragma unroll
; DI void attn_item(const Params& p, int item, LAS unsigned char* lds, int tid) {
;     ...
;             const bool sel0 = ((msk[0] >> kt) & 1ull) != 0ull, sel1 = ((msk[1] >> kt) & 1ull) != 0ull;
;             const float bias0 = (br || sel0) ? 0.f : -1e30f, bias1 = (br || sel1) ? 0.f : -1e30f;
;             const bool act0 = br || (__builtin_amdgcn_ballot_w64(sel0) != 0ull), act1 = br || (__builtin_amdgcn_ballot_w64(sel1) != 0ull);
;             const bool edge = (kt == tile) || (br && kt == tile - 8);
;             if (act0 && act1) attn_tile<3>(Kl, Vl, q, O, m, l, bias0, bias1, edge, br, kt, t0, tl, i16, quad);
;             else if (act0) attn_tile<1>(Kl, Vl, q, O, m, l, bias0, bias1, edge, br, kt, t0, tl, i16, quad);
;             else if (act1) attn_tile<2>(Kl, Vl, q, O, m, l, bias0, bias1, edge, br, kt, t0, tl, i16, quad);
.LBB0_343:
	s_mul_i32 s4, s11, 0x8c00
	s_or_b64 s[6:7], s[52:53], s[6:7]
	s_add_i32 s62, s4, 0
	s_xor_b64 s[4:5], s[52:53], -1
	v_cndmask_b32_e64 v112, v226, 0, s[6:7]
	s_or_b64 s[6:7], s[52:53], s[8:9]
	s_cmp_lg_u32 s54, s56
	v_cndmask_b32_e64 v116, v226, 0, s[6:7]
	s_cselect_b64 s[6:7], -1, 0
	s_cmp_lg_u32 s54, s57
	s_cselect_b64 s[8:9], -1, 0
	s_or_b64 s[4:5], s[4:5], s[8:9]
	s_and_b64 s[8:9], s[24:25], s[48:49]
	s_andn2_b64 vcc, exec, s[8:9]
	s_and_b64 s[8:9], s[6:7], s[4:5]
	s_cbranch_vccz .LBB0_363
	s_xor_b64 s[4:5], s[24:25], -1
	s_mov_b64 s[6:7], -1
	s_and_b64 vcc, exec, s[4:5]
	s_cbranch_vccz .LBB0_354
	v_mov_b64_e32 v[148:149], v[82:83]
	v_mov_b64_e32 v[144:145], v[86:87]
	v_mov_b64_e32 v[140:141], v[90:91]
	v_mov_b64_e32 v[136:137], v[94:95]
	v_mov_b64_e32 v[132:133], v[98:99]
	v_mov_b64_e32 v[128:129], v[102:103]
	v_mov_b64_e32 v[124:125], v[106:107]
	v_mov_b64_e32 v[120:121], v[110:111]
	s_andn2_b64 vcc, exec, s[48:49]
	v_mov_b64_e32 v[146:147], v[80:81]
	v_mov_b64_e32 v[142:143], v[84:85]
	v_mov_b64_e32 v[138:139], v[88:89]
	v_mov_b64_e32 v[134:135], v[92:93]
	v_mov_b64_e32 v[130:131], v[96:97]
	v_mov_b64_e32 v[126:127], v[100:101]
	v_mov_b64_e32 v[122:123], v[104:105]
	v_mov_b64_e32 v[118:119], v[108:109]
	v_mov_b32_e32 v248, v198
	v_mov_b32_e32 v247, v244
	s_cbranch_vccnz .LBB0_353
	v_add_u32_e32 v113, s62, v229
	v_add_u32_e32 v114, v113, v237
	ds_read_b128 v[120:123], v114
	ds_read_b128 v[124:127], v114 offset:64
	ds_read_b128 v[128:131], v114 offset:128
	ds_read_b128 v[132:135], v114 offset:192
	ds_read_b128 v[136:139], v114 offset:4352
	ds_read_b128 v[140:143], v114 offset:4416
	ds_read_b128 v[144:147], v114 offset:4480
	ds_read_b128 v[148:151], v114 offset:4544
	v_mov_b32_e32 v118, v116
	v_mov_b32_e32 v119, v116
	v_mov_b32_e32 v117, v116
	s_waitcnt lgkmcnt(7)
	s_nop 0
	v_mfma_f32_16x16x32_bf16 v[120:123], v[120:123], v[16:19], v[116:119]
	s_waitcnt lgkmcnt(3)
	v_mfma_f32_16x16x32_bf16 v[136:139], v[136:139], v[16:19], v[116:119]
	v_mfma_f32_16x16x32_bf16 v[120:123], v[124:127], v[24:27], v[120:123]
	s_waitcnt lgkmcnt(2)
	v_mfma_f32_16x16x32_bf16 v[124:127], v[140:143], v[24:27], v[136:139]
	v_mfma_f32_16x16x32_bf16 v[120:123], v[128:131], v[20:23], v[120:123]
	s_waitcnt lgkmcnt(1)
	v_mfma_f32_16x16x32_bf16 v[124:127], v[144:147], v[20:23], v[124:127]
	v_mfma_f32_16x16x32_bf16 v[158:161], v[132:135], v[28:31], v[120:123]
	s_waitcnt lgkmcnt(0)
	v_mfma_f32_16x16x32_bf16 v[142:145], v[148:151], v[28:31], v[124:127]
	s_nop 2
	ds_read_b128 v[120:123], v114 offset:8704
	s_nop 0
	ds_read_b128 v[124:127], v114 offset:8768
	ds_read_b128 v[128:131], v114 offset:8832
	ds_read_b128 v[132:135], v114 offset:8896
	ds_read_b128 v[136:139], v114 offset:13056
	ds_read_b128 v[146:149], v114 offset:13120
	ds_read_b128 v[150:153], v114 offset:13184
	ds_read_b128 v[154:157], v114 offset:13248
	s_waitcnt lgkmcnt(7)
	v_mfma_f32_16x16x32_bf16 v[120:123], v[120:123], v[16:19], v[116:119]
	v_add_u32_e32 v113, v113, v238
	s_waitcnt lgkmcnt(3)
	v_mfma_f32_16x16x32_bf16 v[136:139], v[136:139], v[16:19], v[116:119]
	v_mfma_f32_16x16x32_bf16 v[118:121], v[124:127], v[24:27], v[120:123]
	s_waitcnt lgkmcnt(2)
	v_mfma_f32_16x16x32_bf16 v[122:125], v[146:149], v[24:27], v[136:139]
	v_mfma_f32_16x16x32_bf16 v[118:121], v[128:131], v[20:23], v[118:121]
	s_waitcnt lgkmcnt(1)
	v_mfma_f32_16x16x32_bf16 v[122:125], v[150:153], v[20:23], v[122:125]
	v_mfma_f32_16x16x32_bf16 v[162:165], v[132:135], v[28:31], v[118:121]
	s_waitcnt lgkmcnt(0)
	v_mfma_f32_16x16x32_bf16 v[118:121], v[154:157], v[28:31], v[122:125]
	ds_read_b128 v[146:149], v113 offset:17408
	ds_read_b128 v[154:157], v113 offset:19712
	ds_read_b128 v[150:153], v113 offset:22016
	ds_read_b128 v[138:141], v113 offset:24320
	ds_read_b128 v[130:133], v113 offset:26624
	ds_read_b128 v[134:137], v113 offset:28928
	ds_read_b128 v[126:129], v113 offset:31232
	ds_read_b128 v[122:125], v113 offset:33536
	s_andn2_b64 vcc, exec, s[8:9]
	s_cbranch_vccnz .LBB0_348
	v_max3_f32 v113, v158, v159, s97
	v_max3_f32 v113, v113, v160, v161
	v_max3_f32 v113, v113, v142, v143
	v_max3_f32 v113, v113, v144, v145
	v_max3_f32 v113, v113, v162, v163
	v_max3_f32 v113, v113, v164, v165
	v_max3_f32 v113, v113, v118, v119
	v_max3_f32 v113, v113, v120, v121
	s_mov_b64 s[6:7], 0

; template <int MASK> ...
;     ...
;         tmx = xq_max(tmx);
;         const float mnew = (tmx > m[rt] + 8.f) ? tmx : m[rt];
;         const float corr = __builtin_amdgcn_exp2f(m[rt] - mnew);
;         float psum = 0.f;
; #pragma unroll
;         for (int nt = 0; nt < 4; ++nt)
; #pragma unroll
;             for (int r = 0; r < 4; ++r) { const float pe = __builtin_amdgcn_exp2f(s[rt][nt][r] - mnew); s[rt][nt][r] = pe; psum += pe; }
;         l[rt] = l[rt] * corr + psum; m[rt] = mnew;
;         if (__builtin_amdgcn_ballot_w64(corr != 1.f) != 0ull) {
; #pragma unroll
;             for (int dt = 0; dt < 8; ++dt) O[rt][dt] *= corr;
;         }
.LBB0_350:
	v_mov_b32_e32 v114, v113
	s_nop 1
	v_permlane16_swap_b32_e32 v113, v114
	v_max_f32_e32 v113, v113, v114
	v_mov_b32_e32 v114, v113
	s_nop 1
	v_permlane32_swap_b32_e32 v113, v114
	v_max_f32_e32 v113, v113, v114
	v_add_f32_e32 v114, 0x41000000, v244
	v_cmp_gt_f32_e32 vcc, v113, v114
	v_mov_b64_e32 v[188:189], v[110:111]
	v_mov_b64_e32 v[196:197], v[106:107]
	v_cndmask_b32_e32 v247, v244, v113, vcc
	v_sub_f32_e32 v113, v244, v247
	v_exp_f32_e32 v114, v113
	v_mov_b64_e32 v[192:193], v[102:103]
	v_mov_b64_e32 v[184:185], v[98:99]
	v_mov_b64_e32 v[180:181], v[94:95]
	v_mov_b64_e32 v[176:177], v[90:91]
	v_mov_b64_e32 v[172:173], v[86:87]
	v_mov_b64_e32 v[168:169], v[82:83]
	v_cmp_neq_f32_e32 vcc, 1.0, v114
	v_mov_b64_e32 v[186:187], v[108:109]
	v_mov_b64_e32 v[194:195], v[104:105]
	v_mov_b64_e32 v[190:191], v[100:101]
	v_mov_b64_e32 v[182:183], v[96:97]
	v_mov_b64_e32 v[178:179], v[92:93]
	v_mov_b64_e32 v[174:175], v[88:89]
	v_mov_b64_e32 v[170:171], v[84:85]
	v_mov_b64_e32 v[166:167], v[80:81]
	s_cbranch_vccz .LBB0_352
	v_pk_mul_f32 v[168:169], v[82:83], v[114:115] op_sel_hi:[1,0]
	v_pk_mul_f32 v[166:167], v[80:81], v[114:115] op_sel_hi:[1,0]
	v_pk_mul_f32 v[172:173], v[86:87], v[114:115] op_sel_hi:[1,0]
	v_pk_mul_f32 v[170:171], v[84:85], v[114:115] op_sel_hi:[1,0]
	v_pk_mul_f32 v[176:177], v[90:91], v[114:115] op_sel_hi:[1,0]
	v_pk_mul_f32 v[174:175], v[88:89], v[114:115] op_sel_hi:[1,0]
	v_pk_mul_f32 v[180:181], v[94:95], v[114:115] op_sel_hi:[1,0]
	v_pk_mul_f32 v[178:179], v[92:93], v[114:115] op_sel_hi:[1,0]
	v_pk_mul_f32 v[184:185], v[98:99], v[114:115] op_sel_hi:[1,0]
	v_pk_mul_f32 v[182:183], v[96:97], v[114:115] op_sel_hi:[1,0]
	v_pk_mul_f32 v[192:193], v[102:103], v[114:115] op_sel_hi:[1,0]
	v_pk_mul_f32 v[190:191], v[100:101], v[114:115] op_sel_hi:[1,0]
	v_pk_mul_f32 v[196:197], v[106:107], v[114:115] op_sel_hi:[1,0]
	v_pk_mul_f32 v[194:195], v[104:105], v[114:115] op_sel_hi:[1,0]
	v_pk_mul_f32 v[188:189], v[110:111], v[114:115] op_sel_hi:[1,0]
	v_pk_mul_f32 v[186:187], v[108:109], v[114:115] op_sel_hi:[1,0]

; #define LAS __attribute__((address_space(3)))
; template <int MASK> ...
;     ...
;     for (int np = 0; np < 2; ++np) {
;         bf16x8 kf[2][4];
; #pragma unroll
;         for (int n2 = 0; n2 < 2; ++n2)
; #pragma unroll
;             for (int kk = 0; kk < 4; ++kk) kf[n2][kk] = *(const LAS bf16x8*)(Kl + ((np * 2 + n2) * 16 + i16) * 136 + kk * 32 + quad * 8);
;         __builtin_amdgcn_sched_barrier(0);
; #pragma unroll
;         for (int n2 = 0; n2 < 2; ++n2) { s[0][np * 2 + n2] = (f32x4){bias0, bias0, bias0, bias0}; s[1][np * 2 + n2] = (f32x4){bias1, bias1, bias1, bias1}; }
; #pragma unroll
;         for (int kk = 0; kk < 4; ++kk)
; #pragma unroll
;             for (int n2 = 0; n2 < 2; ++n2) {
;                 if (MASK & 1) s[0][np * 2 + n2] = __builtin_amdgcn_mfma_f32_16x16x32_bf16(kf[n2][kk], q[0][kk], s[0][np * 2 + n2], 0, 0, 0);
;                 if (MASK & 2) s[1][np * 2 + n2] = __builtin_amdgcn_mfma_f32_16x16x32_bf16(kf[n2][kk], q[1][kk], s[1][np * 2 + n2], 0, 0, 0); }
;     }
;     u32x2 vlo0[8], vhi0[8];
; #pragma unroll
;     for (int dt = 0; dt < 8; ++dt) { const u32x4 vq = *(const LAS u32x4*)(Vl + (dt * 16 + i16) * 72 + quad * 8); vlo0[dt] = (u32x2){vq.x, vq.y}; vhi0[dt] = (u32x2){vq.z, vq.w}; }
;     __builtin_amdgcn_sched_barrier(0);
;     bf16x8 pa[2][2];
; #pragma unroll
;     for (int rt = 0; rt < 2; ++rt) {
;         if (!(MASK & (1 << rt))) continue;
;         const int t = t0 + rt * 4 + tl;
;         float tmx = -1e30f;
;         if (edge) {
; #pragma unroll
;             for (int nt = 0; nt < 4; ++nt)
; #pragma unroll
;                 for (int r = 0; r < 4; ++r) { const int key = kt * 64 + nt * 16 + quad * 4 + r;
;                     const bool ok = (key <= t) && (br ? (key > t - 512) : true);
;                     const float sv = ok ? s[rt][nt][r] : -1e30f; s[rt][nt][r] = sv; tmx = fmaxf(tmx, sv); }
;         } else {
; #pragma unroll
;             for (int nt = 0; nt < 4; ++nt) tmx = fmaxf(fmaxf(tmx, fmaxf(s[rt][nt][0], s[rt][nt][1])), fmaxf(s[rt][nt][2], s[rt][nt][3]));
;         }
.LBB0_354:
	v_mov_b64_e32 v[168:169], v[78:79]
	v_mov_b64_e32 v[172:173], v[74:75]
	v_mov_b64_e32 v[176:177], v[70:71]
	v_mov_b64_e32 v[180:181], v[62:63]
	v_mov_b64_e32 v[164:165], v[50:51]
	v_mov_b64_e32 v[160:161], v[54:55]
	v_mov_b64_e32 v[156:157], v[58:59]
	v_mov_b64_e32 v[152:153], v[66:67]
	s_andn2_b64 vcc, exec, s[6:7]
	v_mov_b64_e32 v[166:167], v[76:77]
	v_mov_b64_e32 v[170:171], v[72:73]
	v_mov_b64_e32 v[174:175], v[68:69]
	v_mov_b64_e32 v[178:179], v[60:61]
	v_mov_b64_e32 v[162:163], v[48:49]
	v_mov_b64_e32 v[158:159], v[52:53]
	v_mov_b64_e32 v[154:155], v[56:57]
	v_mov_b64_e32 v[150:151], v[64:65]
	v_mov_b32_e32 v249, v243
	v_mov_b32_e32 v246, v245
	s_cbranch_vccnz .LBB0_362
	v_add_u32_e32 v117, s62, v229
	v_add_u32_e32 v150, v117, v237
	ds_read_b128 v[118:121], v150
	ds_read_b128 v[122:125], v150 offset:64
	ds_read_b128 v[126:129], v150 offset:128
	ds_read_b128 v[130:133], v150 offset:192
	ds_read_b128 v[134:137], v150 offset:4352
	ds_read_b128 v[138:141], v150 offset:4416
	ds_read_b128 v[142:145], v150 offset:4480
	ds_read_b128 v[146:149], v150 offset:4544
	v_mov_b32_e32 v113, v112
	v_mov_b32_e32 v114, v112
	v_mov_b32_e32 v115, v112
	s_waitcnt lgkmcnt(7)
	s_nop 0
	v_mfma_f32_16x16x32_bf16 v[118:121], v[118:121], v[0:3], v[112:115]
	s_waitcnt lgkmcnt(3)
	v_mfma_f32_16x16x32_bf16 v[134:137], v[134:137], v[0:3], v[112:115]
	v_mfma_f32_16x16x32_bf16 v[118:121], v[122:125], v[8:11], v[118:121]
	s_waitcnt lgkmcnt(2)
	v_mfma_f32_16x16x32_bf16 v[122:125], v[138:141], v[8:11], v[134:137]
	v_mfma_f32_16x16x32_bf16 v[118:121], v[126:129], v[4:7], v[118:121]
	s_waitcnt lgkmcnt(1)
	v_mfma_f32_16x16x32_bf16 v[122:125], v[142:145], v[4:7], v[122:125]
	v_mfma_f32_16x16x32_bf16 v[158:161], v[130:133], v[12:15], v[118:121]
	s_waitcnt lgkmcnt(0)
	v_mfma_f32_16x16x32_bf16 v[142:145], v[146:149], v[12:15], v[122:125]
	s_nop 2
	ds_read_b128 v[118:121], v150 offset:8704
	s_nop 0
	ds_read_b128 v[122:125], v150 offset:8768
	ds_read_b128 v[126:129], v150 offset:8832
	ds_read_b128 v[130:133], v150 offset:8896
	ds_read_b128 v[134:137], v150 offset:13056
	ds_read_b128 v[138:141], v150 offset:13120
	ds_read_b128 v[146:149], v150 offset:13184
	ds_read_b128 v[150:153], v150 offset:13248
	s_waitcnt lgkmcnt(7)
	v_mfma_f32_16x16x32_bf16 v[118:121], v[118:121], v[0:3], v[112:115]
	s_waitcnt lgkmcnt(3)
	v_mfma_f32_16x16x32_bf16 v[134:137], v[134:137], v[0:3], v[112:115]
	v_mfma_f32_16x16x32_bf16 v[118:121], v[122:125], v[8:11], v[118:121]
	s_nop 1
	v_add_u32_e32 v113, v117, v238
	s_waitcnt lgkmcnt(2)
	v_mfma_f32_16x16x32_bf16 v[122:125], v[138:141], v[8:11], v[134:137]
	v_mfma_f32_16x16x32_bf16 v[118:121], v[126:129], v[4:7], v[118:121]
	s_waitcnt lgkmcnt(1)
	v_mfma_f32_16x16x32_bf16 v[122:125], v[146:149], v[4:7], v[122:125]
	v_mfma_f32_16x16x32_bf16 v[162:165], v[130:133], v[12:15], v[118:121]
	s_waitcnt lgkmcnt(0)
	v_mfma_f32_16x16x32_bf16 v[118:121], v[150:153], v[12:15], v[122:125]
	ds_read_b128 v[146:149], v113 offset:17408
	ds_read_b128 v[154:157], v113 offset:19712
	ds_read_b128 v[150:153], v113 offset:22016
	ds_read_b128 v[138:141], v113 offset:24320
	ds_read_b128 v[130:133], v113 offset:26624
	ds_read_b128 v[134:137], v113 offset:28928
	ds_read_b128 v[126:129], v113 offset:31232
	ds_read_b128 v[122:125], v113 offset:33536
	s_andn2_b64 vcc, exec, s[8:9]
	s_mov_b64 s[6:7], -1
	s_cbranch_vccnz .LBB0_357
	v_max3_f32 v113, v158, v159, s97
	v_max3_f32 v113, v113, v160, v161
	v_max3_f32 v113, v113, v142, v143
	v_max3_f32 v113, v113, v144, v145
	v_max3_f32 v113, v113, v162, v163
	v_max3_f32 v113, v113, v164, v165
	v_max3_f32 v113, v113, v118, v119
	v_max3_f32 v113, v113, v120, v121
	s_mov_b64 s[6:7], 0

; template <int MASK> ...
;     ...
;         tmx = xq_max(tmx);
;         const float mnew = (tmx > m[rt] + 8.f) ? tmx : m[rt];
;         const float corr = __builtin_amdgcn_exp2f(m[rt] - mnew);
;         float psum = 0.f;
; #pragma unroll
;         for (int nt = 0; nt < 4; ++nt)
; #pragma unroll
;             for (int r = 0; r < 4; ++r) { const float pe = __builtin_amdgcn_exp2f(s[rt][nt][r] - mnew); s[rt][nt][r] = pe; psum += pe; }
;         l[rt] = l[rt] * corr + psum; m[rt] = mnew;
;         if (__builtin_amdgcn_ballot_w64(corr != 1.f) != 0ull) {
; #pragma unroll
;             for (int dt = 0; dt < 8; ++dt) O[rt][dt] *= corr;
;         }
.LBB0_359:
	v_mov_b32_e32 v114, v113
	s_nop 1
	v_permlane16_swap_b32_e32 v113, v114
	v_max_f32_e32 v113, v113, v114
	v_mov_b32_e32 v114, v113
	s_nop 1
	v_permlane32_swap_b32_e32 v113, v114
	v_max_f32_e32 v113, v113, v114
	v_add_f32_e32 v114, 0x41000000, v245
	v_cmp_gt_f32_e32 vcc, v113, v114
	v_mov_b64_e32 v[188:189], v[66:67]
	v_mov_b64_e32 v[196:197], v[58:59]
	v_cndmask_b32_e32 v246, v245, v113, vcc
	v_sub_f32_e32 v113, v245, v246
	v_exp_f32_e32 v114, v113
	v_mov_b64_e32 v[192:193], v[54:55]
	v_mov_b64_e32 v[184:185], v[50:51]
	v_mov_b64_e32 v[180:181], v[62:63]
	v_mov_b64_e32 v[176:177], v[70:71]
	v_mov_b64_e32 v[172:173], v[74:75]
	v_mov_b64_e32 v[168:169], v[78:79]
	v_cmp_neq_f32_e32 vcc, 1.0, v114
	v_mov_b64_e32 v[186:187], v[64:65]
	v_mov_b64_e32 v[194:195], v[56:57]
	v_mov_b64_e32 v[190:191], v[52:53]
	v_mov_b64_e32 v[182:183], v[48:49]
	v_mov_b64_e32 v[178:179], v[60:61]
	v_mov_b64_e32 v[174:175], v[68:69]
	v_mov_b64_e32 v[170:171], v[72:73]
	v_mov_b64_e32 v[166:167], v[76:77]
	s_cbranch_vccz .LBB0_361
	v_pk_mul_f32 v[168:169], v[78:79], v[114:115] op_sel_hi:[1,0]
	v_pk_mul_f32 v[166:167], v[76:77], v[114:115] op_sel_hi:[1,0]
	v_pk_mul_f32 v[172:173], v[74:75], v[114:115] op_sel_hi:[1,0]
	v_pk_mul_f32 v[170:171], v[72:73], v[114:115] op_sel_hi:[1,0]
	v_pk_mul_f32 v[176:177], v[70:71], v[114:115] op_sel_hi:[1,0]
	v_pk_mul_f32 v[174:175], v[68:69], v[114:115] op_sel_hi:[1,0]
	v_pk_mul_f32 v[180:181], v[62:63], v[114:115] op_sel_hi:[1,0]
	v_pk_mul_f32 v[178:179], v[60:61], v[114:115] op_sel_hi:[1,0]
	v_pk_mul_f32 v[184:185], v[50:51], v[114:115] op_sel_hi:[1,0]
	v_pk_mul_f32 v[182:183], v[48:49], v[114:115] op_sel_hi:[1,0]
	v_pk_mul_f32 v[192:193], v[54:55], v[114:115] op_sel_hi:[1,0]
	v_pk_mul_f32 v[190:191], v[52:53], v[114:115] op_sel_hi:[1,0]
	v_pk_mul_f32 v[196:197], v[58:59], v[114:115] op_sel_hi:[1,0]
	v_pk_mul_f32 v[194:195], v[56:57], v[114:115] op_sel_hi:[1,0]
	v_pk_mul_f32 v[188:189], v[66:67], v[114:115] op_sel_hi:[1,0]
	v_pk_mul_f32 v[186:187], v[64:65], v[114:115] op_sel_hi:[1,0]

; #define LAS __attribute__((address_space(3)))
; template <int MASK> ...
;     ...
;     for (int np = 0; np < 2; ++np) {
;         bf16x8 kf[2][4];
; #pragma unroll
;         for (int n2 = 0; n2 < 2; ++n2)
; #pragma unroll
;             for (int kk = 0; kk < 4; ++kk) kf[n2][kk] = *(const LAS bf16x8*)(Kl + ((np * 2 + n2) * 16 + i16) * 136 + kk * 32 + quad * 8);
;         __builtin_amdgcn_sched_barrier(0);
; #pragma unroll
;         for (int n2 = 0; n2 < 2; ++n2) { s[0][np * 2 + n2] = (f32x4){bias0, bias0, bias0, bias0}; s[1][np * 2 + n2] = (f32x4){bias1, bias1, bias1, bias1}; }
; #pragma unroll
;         for (int kk = 0; kk < 4; ++kk)
; #pragma unroll
;             for (int n2 = 0; n2 < 2; ++n2) {
;                 if (MASK & 1) s[0][np * 2 + n2] = __builtin_amdgcn_mfma_f32_16x16x32_bf16(kf[n2][kk], q[0][kk], s[0][np * 2 + n2], 0, 0, 0);
;                 if (MASK & 2) s[1][np * 2 + n2] = __builtin_amdgcn_mfma_f32_16x16x32_bf16(kf[n2][kk], q[1][kk], s[1][np * 2 + n2], 0, 0, 0); }
;     }
;     u32x2 vlo0[8], vhi0[8];
; #pragma unroll
;     for (int dt = 0; dt < 8; ++dt) { const u32x4 vq = *(const LAS u32x4*)(Vl + (dt * 16 + i16) * 72 + quad * 8); vlo0[dt] = (u32x2){vq.x, vq.y}; vhi0[dt] = (u32x2){vq.z, vq.w}; }
;     __builtin_amdgcn_sched_barrier(0);
;     bf16x8 pa[2][2];
; #pragma unroll
;     for (int rt = 0; rt < 2; ++rt) {
;         if (!(MASK & (1 << rt))) continue;
;         const int t = t0 + rt * 4 + tl;
;         float tmx = -1e30f;
;         if (edge) {
; #pragma unroll
;             for (int nt = 0; nt < 4; ++nt)
; #pragma unroll
;                 for (int r = 0; r < 4; ++r) { const int key = kt * 64 + nt * 16 + quad * 4 + r;
;                     const bool ok = (key <= t) && (br ? (key > t - 512) : true);
;                     const float sv = ok ? s[rt][nt][r] : -1e30f; s[rt][nt][r] = sv; tmx = fmaxf(tmx, sv); }
;         } else {
; #pragma unroll
;             for (int nt = 0; nt < 4; ++nt) tmx = fmaxf(fmaxf(tmx, fmaxf(s[rt][nt][0], s[rt][nt][1])), fmaxf(s[rt][nt][2], s[rt][nt][3]));
;         }
.LBB0_363:
	s_andn2_b64 vcc, exec, s[22:23]
	s_cbranch_vccnz .LBB0_377
	v_add_u32_e32 v176, s62, v229
	v_add_u32_e32 v160, v176, v237
	ds_read_b128 v[120:123], v160
	ds_read_b128 v[124:127], v160 offset:64
	ds_read_b128 v[128:131], v160 offset:128
	ds_read_b128 v[132:135], v160 offset:192
	ds_read_b128 v[136:139], v160 offset:4352
	ds_read_b128 v[140:143], v160 offset:4416
	ds_read_b128 v[144:147], v160 offset:4480
	ds_read_b128 v[148:151], v160 offset:4544
	v_mov_b32_e32 v113, v112
	v_mov_b32_e32 v114, v112
	v_mov_b32_e32 v115, v112
	v_mov_b32_e32 v117, v116
	v_mov_b32_e32 v118, v116
	v_mov_b32_e32 v119, v116
	s_waitcnt lgkmcnt(7)
	v_mfma_f32_16x16x32_bf16 v[152:155], v[120:123], v[0:3], v[112:115]
	v_mfma_f32_16x16x32_bf16 v[120:123], v[120:123], v[16:19], v[116:119]
	s_waitcnt lgkmcnt(3)
	v_mfma_f32_16x16x32_bf16 v[156:159], v[136:139], v[0:3], v[112:115]
	v_mfma_f32_16x16x32_bf16 v[136:139], v[136:139], v[16:19], v[116:119]
	v_mfma_f32_16x16x32_bf16 v[152:155], v[124:127], v[8:11], v[152:155]
	v_mfma_f32_16x16x32_bf16 v[120:123], v[124:127], v[24:27], v[120:123]
	s_waitcnt lgkmcnt(2)
	v_mfma_f32_16x16x32_bf16 v[124:127], v[140:143], v[8:11], v[156:159]
	v_mfma_f32_16x16x32_bf16 v[136:139], v[140:143], v[24:27], v[136:139]
	v_mfma_f32_16x16x32_bf16 v[140:143], v[128:131], v[4:7], v[152:155]
	v_mfma_f32_16x16x32_bf16 v[120:123], v[128:131], v[20:23], v[120:123]
	s_waitcnt lgkmcnt(1)
	v_mfma_f32_16x16x32_bf16 v[124:127], v[144:147], v[4:7], v[124:127]
	v_mfma_f32_16x16x32_bf16 v[128:131], v[144:147], v[20:23], v[136:139]
	v_mfma_f32_16x16x32_bf16 v[152:155], v[132:135], v[12:15], v[140:143]
	v_mfma_f32_16x16x32_bf16 v[172:175], v[132:135], v[28:31], v[120:123]
	s_waitcnt lgkmcnt(0)
	v_mfma_f32_16x16x32_bf16 v[144:147], v[148:151], v[12:15], v[124:127]
	v_mfma_f32_16x16x32_bf16 v[164:167], v[148:151], v[28:31], v[128:131]
	ds_read_b128 v[120:123], v160 offset:8704
	s_nop 0
	ds_read_b128 v[124:127], v160 offset:8768
	ds_read_b128 v[128:131], v160 offset:8832
	ds_read_b128 v[132:135], v160 offset:8896
	ds_read_b128 v[136:139], v160 offset:13056
	ds_read_b128 v[140:143], v160 offset:13120
	ds_read_b128 v[148:151], v160 offset:13184
	ds_read_b128 v[160:163], v160 offset:13248
	s_waitcnt lgkmcnt(7)
	v_mfma_f32_16x16x32_bf16 v[156:159], v[120:123], v[0:3], v[112:115]
	s_waitcnt lgkmcnt(3)
	v_mfma_f32_16x16x32_bf16 v[112:115], v[136:139], v[0:3], v[112:115]
	v_mfma_f32_16x16x32_bf16 v[120:123], v[120:123], v[16:19], v[116:119]
	v_mfma_f32_16x16x32_bf16 v[116:119], v[136:139], v[16:19], v[116:119]
	s_waitcnt lgkmcnt(2)
	v_mfma_f32_16x16x32_bf16 v[112:115], v[140:143], v[8:11], v[112:115]
	v_mfma_f32_16x16x32_bf16 v[136:139], v[124:127], v[8:11], v[156:159]
	v_mfma_f32_16x16x32_bf16 v[120:123], v[124:127], v[24:27], v[120:123]
	v_mfma_f32_16x16x32_bf16 v[116:119], v[140:143], v[24:27], v[116:119]
	s_waitcnt lgkmcnt(1)
	v_mfma_f32_16x16x32_bf16 v[112:115], v[148:151], v[4:7], v[112:115]
	v_mfma_f32_16x16x32_bf16 v[124:127], v[128:131], v[4:7], v[136:139]
	v_mfma_f32_16x16x32_bf16 v[120:123], v[128:131], v[20:23], v[120:123]
	v_mfma_f32_16x16x32_bf16 v[116:119], v[148:151], v[20:23], v[116:119]
	s_waitcnt lgkmcnt(0)
	v_mfma_f32_16x16x32_bf16 v[148:151], v[160:163], v[12:15], v[112:115]
	s_nop 2
	v_add_u32_e32 v112, v176, v238
	v_mfma_f32_16x16x32_bf16 v[156:159], v[132:135], v[12:15], v[124:127]
	v_mfma_f32_16x16x32_bf16 v[168:171], v[132:135], v[28:31], v[120:123]
	v_mfma_f32_16x16x32_bf16 v[160:163], v[160:163], v[28:31], v[116:119]
	ds_read_b128 v[140:143], v112 offset:17408
	ds_read_b128 v[136:139], v112 offset:19712
	ds_read_b128 v[132:135], v112 offset:22016
	ds_read_b128 v[128:131], v112 offset:24320
	ds_read_b128 v[124:127], v112 offset:26624
	ds_read_b128 v[120:123], v112 offset:28928
	ds_read_b128 v[116:119], v112 offset:31232
	ds_read_b128 v[112:115], v112 offset:33536
	s_cmp_eq_u32 s84, 0
	v_cndmask_b32_e64 v176, 0, 1, s[8:9]
	s_cselect_b64 s[22:23], -1, 0
	v_cmp_ne_u32_e64 s[6:7], 1, v176
	s_andn2_b64 vcc, exec, s[8:9]
	s_mov_b64 s[8:9], -1
	s_cbranch_vccnz .LBB0_366
	v_max3_f32 v176, v152, v153, s97
	v_max3_f32 v176, v176, v154, v155
	v_max3_f32 v176, v176, v144, v145
	v_max3_f32 v176, v176, v146, v147
	v_max3_f32 v176, v176, v156, v157
	v_max3_f32 v176, v176, v158, v159
	v_max3_f32 v176, v176, v148, v149
	v_max3_f32 v176, v176, v150, v151
	s_mov_b64 s[8:9], 0

; template <int MASK> ...
;     ...
; #pragma unroll
;             for (int nt = 0; nt < 4; ++nt) tmx = fmaxf(fmaxf(tmx, fmaxf(s[rt][nt][0], s[rt][nt][1])), fmaxf(s[rt][nt][2], s[rt][nt][3]));
;         }
;         tmx = xq_max(tmx);
;         const float mnew = (tmx > m[rt] + 8.f) ? tmx : m[rt];
;         const float corr = __builtin_amdgcn_exp2f(m[rt] - mnew);
;         float psum = 0.f;
; #pragma unroll
;         for (int nt = 0; nt < 4; ++nt)
; #pragma unroll
;             for (int r = 0; r < 4; ++r) { const float pe = __builtin_amdgcn_exp2f(s[rt][nt][r] - mnew); s[rt][nt][r] = pe; psum += pe; }
;         l[rt] = l[rt] * corr + psum; m[rt] = mnew;
;         if (__builtin_amdgcn_ballot_w64(corr != 1.f) != 0ull) {
; #pragma unroll
;             for (int dt = 0; dt < 8; ++dt) O[rt][dt] *= corr;
;         }
.LBB0_368:
	v_mov_b32_e32 v192, v176
	s_nop 1
	v_permlane16_swap_b32_e32 v176, v192
	v_max_f32_e32 v176, v176, v192
	v_mov_b32_e32 v192, v176
	s_nop 1
	v_permlane32_swap_b32_e32 v176, v192
	v_max_f32_e32 v176, v176, v192
	v_add_f32_e32 v192, 0x41000000, v245
	v_cmp_gt_f32_e32 vcc, v176, v192
	s_nop 1
	v_cndmask_b32_e32 v246, v245, v176, vcc
	v_sub_f32_e32 v176, v245, v246
	v_exp_f32_e32 v176, v176
	s_nop 0
	v_cmp_neq_f32_e32 vcc, 1.0, v176
	s_cbranch_vccz .LBB0_370
	v_pk_mul_f32 v[78:79], v[78:79], v[176:177] op_sel_hi:[1,0]
	v_pk_mul_f32 v[76:77], v[76:77], v[176:177] op_sel_hi:[1,0]
	v_pk_mul_f32 v[74:75], v[74:75], v[176:177] op_sel_hi:[1,0]
	v_pk_mul_f32 v[72:73], v[72:73], v[176:177] op_sel_hi:[1,0]
	v_pk_mul_f32 v[70:71], v[70:71], v[176:177] op_sel_hi:[1,0]
	v_pk_mul_f32 v[68:69], v[68:69], v[176:177] op_sel_hi:[1,0]
	v_pk_mul_f32 v[62:63], v[62:63], v[176:177] op_sel_hi:[1,0]
	v_pk_mul_f32 v[60:61], v[60:61], v[176:177] op_sel_hi:[1,0]
	v_pk_mul_f32 v[50:51], v[50:51], v[176:177] op_sel_hi:[1,0]
	v_pk_mul_f32 v[48:49], v[48:49], v[176:177] op_sel_hi:[1,0]
	v_pk_mul_f32 v[54:55], v[54:55], v[176:177] op_sel_hi:[1,0]
	v_pk_mul_f32 v[52:53], v[52:53], v[176:177] op_sel_hi:[1,0]
	v_pk_mul_f32 v[58:59], v[58:59], v[176:177] op_sel_hi:[1,0]
	v_pk_mul_f32 v[56:57], v[56:57], v[176:177] op_sel_hi:[1,0]
	v_pk_mul_f32 v[66:67], v[66:67], v[176:177] op_sel_hi:[1,0]
	v_pk_mul_f32 v[64:65], v[64:65], v[176:177] op_sel_hi:[1,0]
.LBB0_370:
	s_and_b64 vcc, exec, s[6:7]
	s_mov_b64 s[6:7], -1
	s_cbranch_vccnz .LBB0_372
	v_max3_f32 v192, v172, v173, s97
	v_max3_f32 v192, v192, v174, v175
	v_max3_f32 v192, v192, v164, v165
	v_max3_f32 v192, v192, v166, v167
	v_max3_f32 v192, v192, v168, v169
	v_max3_f32 v192, v192, v170, v171
	v_max3_f32 v192, v192, v160, v161
	v_max3_f32 v192, v192, v162, v163
	s_mov_b64 s[6:7], 0

; template <int MASK> ...
;     ...
;         tmx = xq_max(tmx);
;         const float mnew = (tmx > m[rt] + 8.f) ? tmx : m[rt];
;         const float corr = __builtin_amdgcn_exp2f(m[rt] - mnew);
;         float psum = 0.f;
; #pragma unroll
;         for (int nt = 0; nt < 4; ++nt)
; #pragma unroll
;             for (int r = 0; r < 4; ++r) { const float pe = __builtin_amdgcn_exp2f(s[rt][nt][r] - mnew); s[rt][nt][r] = pe; psum += pe; }
;         l[rt] = l[rt] * corr + psum; m[rt] = mnew;
;         if (__builtin_amdgcn_ballot_w64(corr != 1.f) != 0ull) {
; #pragma unroll
;             for (int dt = 0; dt < 8; ++dt) O[rt][dt] *= corr;
;         }
.LBB0_374:
	v_mov_b32_e32 v177, v192
	s_nop 1
	v_permlane16_swap_b32_e32 v192, v177
	v_max_f32_e32 v177, v192, v177
	v_mov_b32_e32 v178, v177
	s_nop 1
	v_permlane32_swap_b32_e32 v177, v178
	v_max_f32_e32 v177, v177, v178
	v_add_f32_e32 v178, 0x41000000, v244
	v_cmp_gt_f32_e32 vcc, v177, v178
	s_nop 1
	v_cndmask_b32_e32 v247, v244, v177, vcc
	v_sub_f32_e32 v177, v244, v247
	v_exp_f32_e32 v178, v177
	s_nop 0
	v_cmp_neq_f32_e32 vcc, 1.0, v178
	s_cbranch_vccz .LBB0_376
	v_pk_mul_f32 v[82:83], v[82:83], v[178:179] op_sel_hi:[1,0]
	v_pk_mul_f32 v[80:81], v[80:81], v[178:179] op_sel_hi:[1,0]
	v_pk_mul_f32 v[86:87], v[86:87], v[178:179] op_sel_hi:[1,0]
	v_pk_mul_f32 v[84:85], v[84:85], v[178:179] op_sel_hi:[1,0]
	v_pk_mul_f32 v[90:91], v[90:91], v[178:179] op_sel_hi:[1,0]
	v_pk_mul_f32 v[88:89], v[88:89], v[178:179] op_sel_hi:[1,0]
	v_pk_mul_f32 v[94:95], v[94:95], v[178:179] op_sel_hi:[1,0]
	v_pk_mul_f32 v[92:93], v[92:93], v[178:179] op_sel_hi:[1,0]
	v_pk_mul_f32 v[98:99], v[98:99], v[178:179] op_sel_hi:[1,0]
	v_pk_mul_f32 v[96:97], v[96:97], v[178:179] op_sel_hi:[1,0]
	v_pk_mul_f32 v[102:103], v[102:103], v[178:179] op_sel_hi:[1,0]
	v_pk_mul_f32 v[100:101], v[100:101], v[178:179] op_sel_hi:[1,0]
	v_pk_mul_f32 v[106:107], v[106:107], v[178:179] op_sel_hi:[1,0]
	v_pk_mul_f32 v[104:105], v[104:105], v[178:179] op_sel_hi:[1,0]
	v_pk_mul_f32 v[110:111], v[110:111], v[178:179] op_sel_hi:[1,0]
	v_pk_mul_f32 v[108:109], v[108:109], v[178:179] op_sel_hi:[1,0]
